# MoBA attention QK: K fragments of key groups 2-4 read one group ahead into free registers, s_nop padding removed
# baseline (speedup 1.0000x reference)
.LBB0_546:
	s_add_i32 s72, s17, 0
	s_lshl_b32 s14, 1, s18
	v_add_u32_e32 v54, s72, v167
	v_and_b32_e32 v50, s14, v128
	v_add_u32_e32 v114, v54, v174
	v_cmp_eq_u32_e32 vcc, 0, v50
	ds_read_b128 v[50:53], v114
	ds_read_b128 v[58:61], v114 offset:2048
	v_and_b32_e32 v55, s14, v129
	v_add_u32_e32 v123, v54, v175
	s_and_b64 s[12:13], s[8:9], vcc
	v_cmp_eq_u32_e32 vcc, 0, v55
	ds_read_b128 v[54:57], v123
	ds_read_b128 v[70:73], v123 offset:2048
	s_and_b64 s[8:9], s[8:9], vcc
	v_cndmask_b32_e64 v62, -v119, v170, s[12:13]
	v_cndmask_b32_e64 v132, -v119, v170, s[8:9]
	v_mov_b32_e32 v63, v62
	v_mov_b32_e32 v64, v62
	v_mov_b32_e32 v65, v62
	v_mov_b32_e32 v133, v132
	v_mov_b32_e32 v134, v132
	v_mov_b32_e32 v135, v132
	ds_read_b128 v[202:205], v114 offset:4096
	ds_read_b128 v[206:209], v114 offset:6144
	ds_read_b128 v[210:213], v123 offset:4096
	ds_read_b128 v[214:217], v123 offset:6144
	s_waitcnt lgkmcnt(4)
	v_mfma_f32_16x16x32_bf16 v[66:69], v[50:53], v[14:17], v[62:65]
	s_andn2_b64 vcc, exec, s[6:7]
	v_mfma_f32_16x16x32_bf16 v[50:53], v[50:53], v[6:9], v[132:135]
	v_mfma_f32_16x16x32_bf16 v[82:85], v[54:57], v[2:5], v[50:53]
	v_mfma_f32_16x16x32_bf16 v[50:53], v[58:61], v[14:17], v[62:65]
	v_mfma_f32_16x16x32_bf16 v[90:93], v[70:73], v[10:13], v[50:53]
	v_mfma_f32_16x16x32_bf16 v[50:53], v[58:61], v[6:9], v[132:135]
	v_mfma_f32_16x16x32_bf16 v[86:89], v[54:57], v[10:13], v[66:69]
	v_mfma_f32_16x16x32_bf16 v[74:77], v[70:73], v[2:5], v[50:53]
	ds_read_b128 v[218:221], v114 offset:8192
	ds_read_b128 v[222:225], v114 offset:10240
	ds_read_b128 v[226:229], v123 offset:8192
	ds_read_b128 v[230:233], v123 offset:10240
	s_waitcnt lgkmcnt(4)
	v_mfma_f32_16x16x32_bf16 v[58:61], v[202:205], v[14:17], v[62:65]
	v_mfma_f32_16x16x32_bf16 v[50:53], v[202:205], v[6:9], v[132:135]
	v_mfma_f32_16x16x32_bf16 v[70:73], v[210:213], v[2:5], v[50:53]
	v_mfma_f32_16x16x32_bf16 v[50:53], v[206:209], v[14:17], v[62:65]
	v_mfma_f32_16x16x32_bf16 v[98:101], v[214:217], v[10:13], v[50:53]
	v_mfma_f32_16x16x32_bf16 v[50:53], v[206:209], v[6:9], v[132:135]
	v_mfma_f32_16x16x32_bf16 v[94:97], v[210:213], v[10:13], v[58:61]
	v_mfma_f32_16x16x32_bf16 v[66:69], v[214:217], v[2:5], v[50:53]
	ds_read_b128 v[234:237], v114 offset:12288
	ds_read_b128 v[140:143], v114 offset:14336
	ds_read_b128 v[144:147], v123 offset:12288
	ds_read_b128 v[148:151], v123 offset:14336
	s_waitcnt lgkmcnt(4)
	v_mfma_f32_16x16x32_bf16 v[58:61], v[218:221], v[14:17], v[62:65]
	v_mfma_f32_16x16x32_bf16 v[50:53], v[218:221], v[6:9], v[132:135]
	v_mfma_f32_16x16x32_bf16 v[102:105], v[226:229], v[10:13], v[58:61]
	v_mfma_f32_16x16x32_bf16 v[58:61], v[226:229], v[2:5], v[50:53]
	v_mfma_f32_16x16x32_bf16 v[50:53], v[222:225], v[14:17], v[62:65]
	v_mfma_f32_16x16x32_bf16 v[106:109], v[230:233], v[10:13], v[50:53]
	v_mfma_f32_16x16x32_bf16 v[50:53], v[222:225], v[6:9], v[132:135]
	v_mfma_f32_16x16x32_bf16 v[54:57], v[230:233], v[2:5], v[50:53]
	s_waitcnt lgkmcnt(0)
	v_mfma_f32_16x16x32_bf16 v[78:81], v[234:237], v[14:17], v[62:65]
	v_mfma_f32_16x16x32_bf16 v[62:65], v[140:143], v[14:17], v[62:65]
	v_mfma_f32_16x16x32_bf16 v[110:113], v[144:147], v[10:13], v[78:81]
	v_mfma_f32_16x16x32_bf16 v[50:53], v[234:237], v[6:9], v[132:135]
	v_mfma_f32_16x16x32_bf16 v[78:81], v[148:151], v[10:13], v[62:65]
	v_mfma_f32_16x16x32_bf16 v[62:65], v[140:143], v[6:9], v[132:135]
	v_mfma_f32_16x16x32_bf16 v[50:53], v[144:147], v[2:5], v[50:53]
	v_mfma_f32_16x16x32_bf16 v[62:65], v[148:151], v[2:5], v[62:65]
	s_cbranch_vccnz .LBB0_548
	v_lshl_or_b32 v114, s16, 7, v116
	v_sub_u32_e32 v114, v152, v114
	s_movk_i32 s64, 0x6f
	v_cmp_lt_i32_e64 s[64:65], s64, v114
	s_movk_i32 s42, 0x41
	s_movk_i32 s44, 0x42
	v_cndmask_b32_e64 v78, v170, v78, s[64:65]
	s_movk_i32 s64, 0x70
	v_cmp_lt_i32_e64 s[64:65], s64, v114
	s_movk_i32 s46, 0x43
	s_movk_i32 s48, 0x50
	v_cndmask_b32_e64 v79, v170, v79, s[64:65]
	s_movk_i32 s64, 0x71
	v_cmp_lt_i32_e64 s[64:65], s64, v114
	s_movk_i32 s50, 0x51
	s_movk_i32 s52, 0x52
	v_cndmask_b32_e64 v80, v170, v80, s[64:65]
	s_movk_i32 s64, 0x72
	v_cmp_lt_i32_e64 s[64:65], s64, v114
	s_movk_i32 s54, 0x53
	s_movk_i32 s56, 0x60
	v_cndmask_b32_e64 v81, v170, v81, s[64:65]
	v_cmp_lt_i32_e64 s[64:65], s95, v114
	s_movk_i32 s58, 0x61
	s_movk_i32 s60, 0x62
	v_cndmask_b32_e64 v82, v170, v82, s[64:65]
	v_cmp_lt_i32_e64 s[64:65], -16, v114
	s_movk_i32 s62, 0x63
	v_cmp_gt_i32_e32 vcc, 0, v114
	v_cndmask_b32_e64 v83, v170, v83, s[64:65]
	v_cmp_lt_i32_e64 s[64:65], -15, v114
	v_cmp_gt_i32_e64 s[6:7], 1, v114
	v_cmp_gt_i32_e64 s[8:9], 2, v114
	v_cmp_gt_i32_e64 s[12:13], 3, v114
	v_cmp_gt_i32_e64 s[14:15], 16, v114
	v_cmp_gt_i32_e64 s[16:17], 17, v114
	v_cmp_gt_i32_e64 s[18:19], 18, v114
	v_cmp_gt_i32_e64 s[20:21], 19, v114
	v_cmp_gt_i32_e64 s[22:23], 32, v114
	v_cmp_gt_i32_e64 s[24:25], 33, v114
	v_cmp_gt_i32_e64 s[26:27], 34, v114
	v_cmp_gt_i32_e64 s[28:29], 35, v114
	v_cmp_gt_i32_e64 s[30:31], 48, v114
	v_cmp_gt_i32_e64 s[34:35], 49, v114
	v_cmp_gt_i32_e64 s[36:37], 50, v114
	v_cmp_gt_i32_e64 s[38:39], 51, v114
	v_cmp_gt_i32_e64 s[40:41], 64, v114
	v_cmp_gt_i32_e64 s[42:43], s42, v114
	v_cmp_gt_i32_e64 s[44:45], s44, v114
	v_cmp_gt_i32_e64 s[46:47], s46, v114
	v_cmp_gt_i32_e64 s[48:49], s48, v114
	v_cmp_gt_i32_e64 s[50:51], s50, v114
	v_cmp_gt_i32_e64 s[52:53], s52, v114
	v_cmp_gt_i32_e64 s[54:55], s54, v114
	v_cmp_gt_i32_e64 s[56:57], s56, v114
	v_cmp_gt_i32_e64 s[58:59], s58, v114
	v_cmp_gt_i32_e64 s[60:61], s60, v114
	v_cmp_gt_i32_e64 s[62:63], s62, v114
	v_cndmask_b32_e64 v84, v170, v84, s[64:65]
	v_cmp_lt_i32_e64 s[64:65], -14, v114
	v_cndmask_b32_e32 v86, v86, v170, vcc
	v_cndmask_b32_e64 v87, v87, v170, s[6:7]
	v_cndmask_b32_e64 v88, v88, v170, s[8:9]
	v_cndmask_b32_e64 v89, v89, v170, s[12:13]
	v_cndmask_b32_e64 v90, v90, v170, s[14:15]
	v_cndmask_b32_e64 v91, v91, v170, s[16:17]
	v_cndmask_b32_e64 v92, v92, v170, s[18:19]
	v_cndmask_b32_e64 v93, v93, v170, s[20:21]
	v_cndmask_b32_e64 v94, v94, v170, s[22:23]
	v_cndmask_b32_e64 v95, v95, v170, s[24:25]
	v_cndmask_b32_e64 v96, v96, v170, s[26:27]
	v_cndmask_b32_e64 v97, v97, v170, s[28:29]
	v_cndmask_b32_e64 v98, v98, v170, s[30:31]
	v_cndmask_b32_e64 v99, v99, v170, s[34:35]
	v_cndmask_b32_e64 v100, v100, v170, s[36:37]
	v_cndmask_b32_e64 v101, v101, v170, s[38:39]
	v_cndmask_b32_e64 v102, v102, v170, s[40:41]
	v_cndmask_b32_e64 v103, v103, v170, s[42:43]
	v_cndmask_b32_e64 v104, v104, v170, s[44:45]
	v_cndmask_b32_e64 v105, v105, v170, s[46:47]
	v_cndmask_b32_e64 v106, v106, v170, s[48:49]
	v_cndmask_b32_e64 v107, v107, v170, s[50:51]
	v_cndmask_b32_e64 v108, v108, v170, s[52:53]
	v_cndmask_b32_e64 v109, v109, v170, s[54:55]
	v_cndmask_b32_e64 v110, v110, v170, s[56:57]
	v_cndmask_b32_e64 v111, v111, v170, s[58:59]
	v_cndmask_b32_e64 v112, v112, v170, s[60:61]
	v_cndmask_b32_e64 v113, v113, v170, s[62:63]
	v_cndmask_b32_e64 v85, v170, v85, s[64:65]
	v_cndmask_b32_e32 v74, v74, v170, vcc
	v_cndmask_b32_e64 v75, v75, v170, s[6:7]
	v_cndmask_b32_e64 v76, v76, v170, s[8:9]
	v_cndmask_b32_e64 v77, v77, v170, s[12:13]
	v_cndmask_b32_e64 v70, v70, v170, s[14:15]
	v_cndmask_b32_e64 v71, v71, v170, s[16:17]
	v_cndmask_b32_e64 v72, v72, v170, s[18:19]
	v_cndmask_b32_e64 v73, v73, v170, s[20:21]
	v_cndmask_b32_e64 v66, v66, v170, s[22:23]
	v_cndmask_b32_e64 v67, v67, v170, s[24:25]
	v_cndmask_b32_e64 v68, v68, v170, s[26:27]
	v_cndmask_b32_e64 v69, v69, v170, s[28:29]
	v_cndmask_b32_e64 v58, v58, v170, s[30:31]
	v_cndmask_b32_e64 v59, v59, v170, s[34:35]
	v_cndmask_b32_e64 v60, v60, v170, s[36:37]
	v_cndmask_b32_e64 v61, v61, v170, s[38:39]
	v_cndmask_b32_e64 v54, v54, v170, s[40:41]
	v_cndmask_b32_e64 v55, v55, v170, s[42:43]
	v_cndmask_b32_e64 v56, v56, v170, s[44:45]
	v_cndmask_b32_e64 v57, v57, v170, s[46:47]
	v_cndmask_b32_e64 v50, v50, v170, s[48:49]
	v_cndmask_b32_e64 v51, v51, v170, s[50:51]
	v_cndmask_b32_e64 v52, v52, v170, s[52:53]
	v_cndmask_b32_e64 v53, v53, v170, s[54:55]
	v_cndmask_b32_e64 v62, v62, v170, s[56:57]
	v_cndmask_b32_e64 v63, v63, v170, s[58:59]
	v_cndmask_b32_e64 v64, v64, v170, s[60:61]
	v_cndmask_b32_e64 v65, v65, v170, s[62:63]
